# v30 plus: layer-1 MLP2 panel sync drops the L2 write-back before the arrival atomic (the exchange is atomics on both sides, already drained by vmcnt(0)+barrier)
# speedup vs baseline: 1.0105x; 1.0105x over previous
; template <int EPI>
; DI void gemm_epilogue(const Params& p, int layer, f32x4 (&acc)[2][2][4][2], int brow, int bcol, int pn, int wr, int wc,
;                       int fr, int fq, char* smem, int ksplit = -1) {
;     ...
;     asm volatile("s_waitcnt vmcnt(0)" ::: "memory");
;     __syncthreads();
;     if (threadIdx.x == 0) {
;       unsigned* cnt = p.cntF + (brow >> 8);
;       __builtin_amdgcn_fence(__ATOMIC_RELEASE, "agent");
;       __hip_atomic_fetch_add(cnt, 1u, __ATOMIC_RELAXED, __HIP_MEMORY_SCOPE_AGENT);
.LBB0_1159:
	s_or_b64 exec, exec, s[16:17]
	s_waitcnt vmcnt(0)
	s_barrier
	s_mov_b64 s[16:17], exec
	v_readlane_b32 s20, v254, 39
	v_readlane_b32 s21, v254, 40
	s_and_b64 s[20:21], s[16:17], s[20:21]
	s_mov_b64 exec, s[20:21]
	s_cbranch_execz .LBB0_1176
	s_mov_b64 s[20:21], exec
	s_ashr_i32 s15, s14, 31
	s_lshl_b64 s[14:15], s[14:15], 2
	v_mbcnt_lo_u32_b32 v2, s20, 0
	s_add_u32 s14, s94, s14
	v_mbcnt_hi_u32_b32 v2, s21, v2
	s_addc_u32 s15, s95, s15
	v_cmp_eq_u32_e32 vcc, 0, v2
	s_and_saveexec_b64 s[22:23], vcc
	s_cbranch_execz .LBB0_1162
	s_bcnt1_i32_b64 s20, s[20:21]
	v_mov_b32_e32 v2, s20
	global_atomic_add v1, v2, s[14:15]
